# attention finalize rewritten by hand: fma form, 8 dwordx4 stores per wave via v_permlane32_swap pairs instead of 16 dwordx2
# speedup vs baseline: 1.0031x; 1.0031x over previous
; #define LAS __attribute__((address_space(3)))
; #define MFMA32(a, b, c) __builtin_amdgcn_mfma_f32_32x32x16_bf16((a), (b), (c), 0, 0, 0)
; __device__ __forceinline__ void attn_phase_fast(LAS unsigned char* lds, const bf16_t* q, const bf16_t* k, const bf16_t* vT, bf16_t* mixed, float lam, const int wave_s) {
;     ...
; #pragma unroll
;             for (int m = 0; m < 2; ++m) {
;                 f32x16 s0, s1;
; #pragma unroll
;                 for (int i = 0; i < 16; ++i) { s0[i] = 0.f; s1[i] = 0.f; }
; #pragma unroll
;                 for (int d0 = 0; d0 < 4; ++d0) {
;                     const int kpos = ((m * 4 + d0) << 5) ^ kxh;
;                     const bf16x8 k0 = *(const LAS bf16x8*)(Kb + kpos), k1 = *(const LAS bf16x8*)(Kb + 32 * KROW + kpos);
;                     const bf16x8 qv = *(const LAS bf16x8*)(Qs + m * 128 + d0 * 32);
;                     s0 = MFMA32(k0, qv, s0); s1 = MFMA32(k1, qv, s1);
;                 }
;                 __builtin_amdgcn_sched_barrier(0);
;                 float ls = 0.f, ls2 = 0.f;
; #pragma unroll
;                 for (int i = 0; i < 16; ++i) { float e0 = __builtin_amdgcn_exp2f(s0[i]), e1 = __builtin_amdgcn_exp2f(s1[i]); asm volatile("" : "+v"(e0), "+v"(e1)); s0[i] = e0; s1[i] = e1; ls += e0; ls2 += e1; }
;                 ls += ls2;
;                 l[m] += ls;
;                 const bf16x8 p0 = packp(s0, 0), p1 = packp(s0, 1), p2 = packp(s1, 0), p3 = packp(s1, 1);
; #pragma unroll
;                 for (int db = 0; db < 4; ++db) {
;                     const LAS unsigned char* vb = Vb + db * 32 * VROW;
;                     const bf16x8 v0 = *(const LAS bf16x8*)(vb + (0 ^ vxh)), v1 = *(const LAS bf16x8*)(vb + (32 ^ vxh)), v2 = *(const LAS bf16x8*)(vb + (64 ^ vxh)), v3 = *(const LAS bf16x8*)(vb + (96 ^ vxh));
;                     o[m][db] = MFMA32(v0, p0, o[m][db]); o[m][db] = MFMA32(v1, p1, o[m][db]); o[m][db] = MFMA32(v2, p2, o[m][db]); o[m][db] = MFMA32(v3, p3, o[m][db]);
;                     if (db == 1) __builtin_amdgcn_sched_barrier(0);
;                 }
.Lattn_skip_tail:
	s_waitcnt lgkmcnt(7)
	v_mfma_f32_32x32x16_bf16 v[128:143], v[144:147], v[180:183], 0
	ds_read_b128 v[216:219], v228 offset:128
	s_add_i32 m0, s22, 0x8000
	s_nop 0
	global_load_lds_dwordx4 v208, s[6:7]
	s_waitcnt lgkmcnt(7)
	v_mfma_f32_32x32x16_bf16 v[128:143], v[148:151], v[184:187], v[128:143]
	ds_read_b128 v[220:223], v228 offset:160
	s_add_i32 m0, s24, 0x8000
	s_nop 0
	global_load_lds_dwordx4 v209, s[2:3]
	s_waitcnt lgkmcnt(7)
	v_mfma_f32_32x32x16_bf16 v[128:143], v[152:155], v[188:191], v[128:143]
	ds_read_b128 v[224:227], v228 offset:192
	s_add_i32 m0, s26, 0x8000
	s_nop 0
	global_load_lds_dwordx4 v210, s[6:7]
	s_waitcnt lgkmcnt(7)
	v_mfma_f32_32x32x16_bf16 v[128:143], v[156:159], v[192:195], v[128:143]
	ds_read_b128 v[234:237], v228 offset:224
	s_add_i32 m0, s27, 0x8000
	s_nop 0
	global_load_lds_dwordx4 v211, s[2:3]
	s_add_u32 s6, s6, 0x10000
	s_addc_u32 s7, s7, 0
	s_add_u32 s2, s2, 0x80
	s_addc_u32 s3, s3, 0
	s_waitcnt lgkmcnt(7)
	v_mfma_f32_32x32x16_bf16 v[144:159], v[164:167], v[180:183], 0
	ds_read_b128 v[180:183], v200
	ds_read_b128 v[238:241], v200 offset:8192
	v_exp_f32_e32 v128, v128
	v_exp_f32_e32 v129, v129
	v_add_f32_e32 v162, v162, v128
	v_exp_f32_e32 v130, v130
	s_waitcnt lgkmcnt(8)
	v_mfma_f32_32x32x16_bf16 v[144:159], v[168:171], v[184:187], v[144:159]
	ds_read_b128 v[184:187], v201
	ds_read_b128 v[242:245], v201 offset:8192
	v_add_f32_e32 v162, v162, v129
	v_exp_f32_e32 v131, v131
	v_add_f32_e32 v162, v162, v130
	v_cvt_pk_bf16_f32 v128, v128, v129
	s_waitcnt lgkmcnt(9)
	v_mfma_f32_32x32x16_bf16 v[144:159], v[172:175], v[188:191], v[144:159]
	ds_read_b128 v[188:191], v202
	ds_read_b128 v[246:249], v202 offset:8192
	v_exp_f32_e32 v132, v132
	v_add_f32_e32 v162, v162, v131
	v_exp_f32_e32 v133, v133
	v_add_f32_e32 v162, v162, v132
	s_waitcnt lgkmcnt(10)
	v_mfma_f32_32x32x16_bf16 v[144:159], v[212:215], v[192:195], v[144:159]
	ds_read_b128 v[192:195], v203
	ds_read_b128 v[212:215], v203 offset:8192
	v_cvt_pk_bf16_f32 v129, v130, v131
	v_exp_f32_e32 v134, v134
	v_add_f32_e32 v162, v162, v133
	v_exp_f32_e32 v135, v135
	s_waitcnt lgkmcnt(7)
	v_mfma_f32_32x32x16_bf16 v[164:179], v[180:183], v[216:219], 0
	ds_read_b128 v[250:253], v204
	v_add_f32_e32 v162, v162, v134
	v_cvt_pk_bf16_f32 v130, v132, v133
	v_exp_f32_e32 v136, v136
	v_add_f32_e32 v162, v162, v135
	s_waitcnt lgkmcnt(6)
	v_mfma_f32_32x32x16_bf16 v[164:179], v[184:187], v[220:223], v[164:179]
	v_exp_f32_e32 v137, v137
	v_add_f32_e32 v162, v162, v136
	v_cvt_pk_bf16_f32 v131, v134, v135
	v_exp_f32_e32 v138, v138
	s_waitcnt lgkmcnt(4)
	v_mfma_f32_32x32x16_bf16 v[164:179], v[188:191], v[224:227], v[164:179]
	v_add_f32_e32 v162, v162, v137
	v_exp_f32_e32 v139, v139
	v_add_f32_e32 v162, v162, v138
	v_cvt_pk_bf16_f32 v132, v136, v137
	s_waitcnt lgkmcnt(2)
	v_mfma_f32_32x32x16_bf16 v[164:179], v[192:195], v[234:237], v[164:179]
	v_exp_f32_e32 v140, v140
	v_add_f32_e32 v162, v162, v139
	v_exp_f32_e32 v141, v141
	v_add_f32_e32 v162, v162, v140
	v_mfma_f32_32x32x16_bf16 v[180:195], v[238:241], v[216:219], 0
	ds_read_b128 v[216:219], v204 offset:4096
	ds_read_b128 v[238:241], v204 offset:8192
	v_cvt_pk_bf16_f32 v133, v138, v139
	v_exp_f32_e32 v142, v142
	v_add_f32_e32 v162, v162, v141
	v_exp_f32_e32 v143, v143
	v_mfma_f32_32x32x16_bf16 v[180:195], v[242:245], v[220:223], v[180:195]
	ds_read_b128 v[220:223], v204 offset:12288
	ds_read_b128 v[242:245], v205
	v_add_f32_e32 v162, v162, v142
	v_cvt_pk_bf16_f32 v134, v140, v141
	v_add_f32_e32 v162, v162, v143
	v_cvt_pk_bf16_f32 v135, v142, v143
	v_mfma_f32_32x32x16_bf16 v[180:195], v[246:249], v[224:227], v[180:195]
	ds_read_b128 v[224:227], v205 offset:4096
	ds_read_b128 v[246:249], v205 offset:8192
	v_exp_f32_e32 v144, v144
	v_exp_f32_e32 v145, v145
	v_add_f32_e32 v162, v162, v144
	v_exp_f32_e32 v146, v146
	s_waitcnt lgkmcnt(7)
	v_mfma_f32_32x32x16_bf16 v[180:195], v[212:215], v[234:237], v[180:195]
	ds_read_b128 v[212:215], v205 offset:12288
	ds_read_b128 v[234:237], v206
	v_add_f32_e32 v162, v162, v145
	v_exp_f32_e32 v147, v147
	v_add_f32_e32 v162, v162, v146
	v_cvt_pk_bf16_f32 v136, v144, v145
	s_waitcnt lgkmcnt(8)
	v_mfma_f32_32x32x16_bf16 v[112:127], v[250:253], v[128:131], v[112:127]
	ds_read_b128 v[250:253], v206 offset:4096
	v_exp_f32_e32 v148, v148
	v_add_f32_e32 v162, v162, v147
	v_exp_f32_e32 v149, v149
	v_add_f32_e32 v162, v162, v148
	s_waitcnt lgkmcnt(8)
	v_mfma_f32_32x32x16_bf16 v[80:95], v[216:219], v[128:131], v[80:95]
	ds_read_b128 v[216:219], v206 offset:8192
	v_cvt_pk_bf16_f32 v137, v146, v147
	v_exp_f32_e32 v150, v150
	v_add_f32_e32 v162, v162, v149
	v_exp_f32_e32 v151, v151
	s_waitcnt lgkmcnt(8)
	v_mfma_f32_32x32x16_bf16 v[48:63], v[238:241], v[128:131], v[48:63]
	ds_read_b128 v[238:241], v206 offset:12288
	v_add_f32_e32 v162, v162, v150
	v_cvt_pk_bf16_f32 v138, v148, v149
	v_exp_f32_e32 v152, v152
	v_add_f32_e32 v162, v162, v151
	s_waitcnt lgkmcnt(8)
	v_mfma_f32_32x32x16_bf16 v[16:31], v[220:223], v[128:131], v[16:31]
	ds_read_b128 v[220:223], v207
	v_exp_f32_e32 v153, v153
	v_add_f32_e32 v162, v162, v152
	v_cvt_pk_bf16_f32 v139, v150, v151
	v_exp_f32_e32 v154, v154
	s_waitcnt lgkmcnt(8)
	v_mfma_f32_32x32x16_bf16 v[112:127], v[242:245], v[132:135], v[112:127]
	ds_read_b128 v[242:245], v207 offset:4096
	v_add_f32_e32 v162, v162, v153
	v_exp_f32_e32 v155, v155
	v_add_f32_e32 v162, v162, v154
	v_cvt_pk_bf16_f32 v140, v152, v153
	s_waitcnt lgkmcnt(8)
	v_mfma_f32_32x32x16_bf16 v[80:95], v[224:227], v[132:135], v[80:95]
	ds_read_b128 v[224:227], v207 offset:8192
	v_exp_f32_e32 v156, v156
	v_add_f32_e32 v162, v162, v155
	v_exp_f32_e32 v157, v157
	v_add_f32_e32 v162, v162, v156
	s_waitcnt lgkmcnt(8)
; #define LAS __attribute__((address_space(3)))
; #define MFMA32(a, b, c) __builtin_amdgcn_mfma_f32_32x32x16_bf16((a), (b), (c), 0, 0, 0)
; __device__ __forceinline__ void attn_phase_fast(LAS unsigned char* lds, const bf16_t* q, const bf16_t* k, const bf16_t* vT, bf16_t* mixed, float lam, const int wave_s) {
;     ...
;                 float ls = 0.f, ls2 = 0.f;
; #pragma unroll
;                 for (int i = 0; i < 16; ++i) { float e0 = __builtin_amdgcn_exp2f(s0[i]), e1 = __builtin_amdgcn_exp2f(s1[i]); asm volatile("" : "+v"(e0), "+v"(e1)); s0[i] = e0; s1[i] = e1; ls += e0; ls2 += e1; }
;                 ls += ls2;
;                 l[m] += ls;
;                 const bf16x8 p0 = packp(s0, 0), p1 = packp(s0, 1), p2 = packp(s1, 0), p3 = packp(s1, 1);
; #pragma unroll
;                 for (int db = 0; db < 4; ++db) {
;                     const LAS unsigned char* vb = Vb + db * 32 * VROW;
;                     const bf16x8 v0 = *(const LAS bf16x8*)(vb + (0 ^ vxh)), v1 = *(const LAS bf16x8*)(vb + (32 ^ vxh)), v2 = *(const LAS bf16x8*)(vb + (64 ^ vxh)), v3 = *(const LAS bf16x8*)(vb + (96 ^ vxh));
;                     o[m][db] = MFMA32(v0, p0, o[m][db]); o[m][db] = MFMA32(v1, p1, o[m][db]); o[m][db] = MFMA32(v2, p2, o[m][db]); o[m][db] = MFMA32(v3, p3, o[m][db]);
;                     if (db == 1) __builtin_amdgcn_sched_barrier(0);
;                 }
;                 __builtin_amdgcn_sched_barrier(0);
;             }
;             asm volatile("s_waitcnt vmcnt(0)" ::: "memory");
;             __syncthreads();
	v_mfma_f32_32x32x16_bf16 v[48:63], v[246:249], v[132:135], v[48:63]
	ds_read_b128 v[246:249], v207 offset:12288
	v_cvt_pk_bf16_f32 v141, v154, v155
	v_exp_f32_e32 v158, v158
	v_add_f32_e32 v162, v162, v157
	v_exp_f32_e32 v159, v159
	s_waitcnt lgkmcnt(8)
	v_mfma_f32_32x32x16_bf16 v[16:31], v[212:215], v[132:135], v[16:31]
	ds_read_b128 v[212:215], v204
	v_add_f32_e32 v162, v162, v158
	v_cvt_pk_bf16_f32 v142, v156, v157
	v_add_f32_e32 v162, v162, v159
	v_cvt_pk_bf16_f32 v143, v158, v159
	s_waitcnt lgkmcnt(8)
	v_mfma_f32_32x32x16_bf16 v[112:127], v[234:237], v[136:139], v[112:127]
	ds_read_b128 v[234:237], v204 offset:4096
	v_exp_f32_e32 v164, v164
	v_exp_f32_e32 v165, v165
	v_add_f32_e32 v163, v163, v164
	v_exp_f32_e32 v166, v166
	s_waitcnt lgkmcnt(8)
	v_mfma_f32_32x32x16_bf16 v[80:95], v[250:253], v[136:139], v[80:95]
	ds_read_b128 v[250:253], v204 offset:8192
	v_add_f32_e32 v163, v163, v165
	v_exp_f32_e32 v167, v167
	v_add_f32_e32 v163, v163, v166
	v_cvt_pk_bf16_f32 v164, v164, v165
	s_waitcnt lgkmcnt(8)
	v_mfma_f32_32x32x16_bf16 v[48:63], v[216:219], v[136:139], v[48:63]
	ds_read_b128 v[216:219], v204 offset:12288
	v_exp_f32_e32 v168, v168
	v_add_f32_e32 v163, v163, v167
	v_exp_f32_e32 v169, v169
	v_add_f32_e32 v163, v163, v168
	s_waitcnt lgkmcnt(8)
	v_mfma_f32_32x32x16_bf16 v[16:31], v[238:241], v[136:139], v[16:31]
	ds_read_b128 v[238:241], v205
	v_cvt_pk_bf16_f32 v165, v166, v167
	v_exp_f32_e32 v170, v170
	v_add_f32_e32 v163, v163, v169
	v_exp_f32_e32 v171, v171
	s_waitcnt lgkmcnt(8)
	v_mfma_f32_32x32x16_bf16 v[112:127], v[220:223], v[140:143], v[112:127]
	ds_read_b128 v[220:223], v205 offset:4096
	v_add_f32_e32 v163, v163, v170
	v_cvt_pk_bf16_f32 v166, v168, v169
	v_exp_f32_e32 v172, v172
	v_add_f32_e32 v163, v163, v171
	s_waitcnt lgkmcnt(8)
	v_mfma_f32_32x32x16_bf16 v[80:95], v[242:245], v[140:143], v[80:95]
	ds_read_b128 v[242:245], v205 offset:8192
	v_exp_f32_e32 v173, v173
	v_add_f32_e32 v163, v163, v172
	v_cvt_pk_bf16_f32 v167, v170, v171
	v_exp_f32_e32 v174, v174
	s_waitcnt lgkmcnt(8)
	v_mfma_f32_32x32x16_bf16 v[48:63], v[224:227], v[140:143], v[48:63]
	ds_read_b128 v[224:227], v205 offset:12288
	v_add_f32_e32 v163, v163, v173
	v_exp_f32_e32 v175, v175
	v_add_f32_e32 v163, v163, v174
	v_cvt_pk_bf16_f32 v168, v172, v173
	s_waitcnt lgkmcnt(8)
	v_mfma_f32_32x32x16_bf16 v[16:31], v[246:249], v[140:143], v[16:31]
	ds_read_b128 v[246:249], v206
	v_exp_f32_e32 v176, v176
	v_add_f32_e32 v163, v163, v175
	v_exp_f32_e32 v177, v177
	v_add_f32_e32 v163, v163, v176
	s_waitcnt lgkmcnt(8)
	v_mfma_f32_32x32x16_bf16 v[96:111], v[212:215], v[164:167], v[96:111]
	ds_read_b128 v[212:215], v206 offset:4096
	v_cvt_pk_bf16_f32 v169, v174, v175
	v_exp_f32_e32 v178, v178
	v_add_f32_e32 v163, v163, v177
	v_exp_f32_e32 v179, v179
	s_waitcnt lgkmcnt(8)
	v_mfma_f32_32x32x16_bf16 v[64:79], v[234:237], v[164:167], v[64:79]
	ds_read_b128 v[234:237], v206 offset:8192
	v_add_f32_e32 v163, v163, v178
	v_cvt_pk_bf16_f32 v170, v176, v177
	v_add_f32_e32 v163, v163, v179
	v_cvt_pk_bf16_f32 v171, v178, v179
	s_waitcnt lgkmcnt(8)
	v_mfma_f32_32x32x16_bf16 v[32:47], v[250:253], v[164:167], v[32:47]
	ds_read_b128 v[250:253], v206 offset:12288
	v_exp_f32_e32 v180, v180
	v_exp_f32_e32 v181, v181
	v_add_f32_e32 v163, v163, v180
	v_exp_f32_e32 v182, v182
	s_waitcnt lgkmcnt(8)
	v_mfma_f32_32x32x16_bf16 v[0:15], v[216:219], v[164:167], v[0:15]
	ds_read_b128 v[216:219], v207
	v_add_f32_e32 v163, v163, v181
	v_exp_f32_e32 v183, v183
	v_add_f32_e32 v163, v163, v182
	v_cvt_pk_bf16_f32 v172, v180, v181
	s_waitcnt lgkmcnt(8)
	v_mfma_f32_32x32x16_bf16 v[96:111], v[238:241], v[168:171], v[96:111]
	ds_read_b128 v[238:241], v207 offset:4096
	v_exp_f32_e32 v184, v184
	v_add_f32_e32 v163, v163, v183
	v_exp_f32_e32 v185, v185
	v_add_f32_e32 v163, v163, v184
	s_waitcnt lgkmcnt(8)
	v_mfma_f32_32x32x16_bf16 v[64:79], v[220:223], v[168:171], v[64:79]
	ds_read_b128 v[220:223], v207 offset:8192
	v_cvt_pk_bf16_f32 v173, v182, v183
	v_exp_f32_e32 v186, v186
	v_add_f32_e32 v163, v163, v185
	v_exp_f32_e32 v187, v187
	s_waitcnt lgkmcnt(8)
	v_mfma_f32_32x32x16_bf16 v[32:47], v[242:245], v[168:171], v[32:47]
	ds_read_b128 v[242:245], v207 offset:12288
	v_add_f32_e32 v163, v163, v186
	v_cvt_pk_bf16_f32 v174, v184, v185
	v_exp_f32_e32 v188, v188
	v_add_f32_e32 v163, v163, v187
	s_waitcnt lgkmcnt(8)
	v_mfma_f32_32x32x16_bf16 v[0:15], v[224:227], v[168:171], v[0:15]
	v_exp_f32_e32 v189, v189
	v_add_f32_e32 v163, v163, v188
	v_cvt_pk_bf16_f32 v175, v186, v187
	v_exp_f32_e32 v190, v190
	s_waitcnt lgkmcnt(7)
	v_mfma_f32_32x32x16_bf16 v[96:111], v[246:249], v[172:175], v[96:111]
	v_add_f32_e32 v163, v163, v189
	v_exp_f32_e32 v191, v191
	v_add_f32_e32 v163, v163, v190
	v_cvt_pk_bf16_f32 v176, v188, v189
	s_waitcnt lgkmcnt(6)
	v_mfma_f32_32x32x16_bf16 v[64:79], v[212:215], v[172:175], v[64:79]
	v_exp_f32_e32 v192, v192
	v_add_f32_e32 v163, v163, v191
	v_exp_f32_e32 v193, v193
	v_add_f32_e32 v163, v163, v192
	s_waitcnt lgkmcnt(5)
	v_mfma_f32_32x32x16_bf16 v[32:47], v[234:237], v[172:175], v[32:47]
	v_cvt_pk_bf16_f32 v177, v190, v191
	v_exp_f32_e32 v194, v194
	v_add_f32_e32 v163, v163, v193
	v_exp_f32_e32 v195, v195
	s_waitcnt lgkmcnt(4)
	v_mfma_f32_32x32x16_bf16 v[0:15], v[250:253], v[172:175], v[0:15]
	v_add_f32_e32 v163, v163, v194
	v_cvt_pk_bf16_f32 v178, v192, v193
	v_add_f32_e32 v163, v163, v195
	v_cvt_pk_bf16_f32 v179, v194, v195
	ds_read_b128 v[180:183], v228
	ds_read_b128 v[184:187], v228 offset:32
	ds_read_b128 v[188:191], v228 offset:64
	ds_read_b128 v[192:195], v228 offset:96
	s_waitcnt lgkmcnt(4)
	s_waitcnt vmcnt(0)
	s_barrier
; __device__ __forceinline__ void attn_phase_fast(LAS unsigned char* lds, const bf16_t* q, const bf16_t* k, const bf16_t* vT, bf16_t* mixed, float lam, const int wave_s) {
;     ...
;                 ATT_DMA(nb, Kg + (size_t)(t + 1) * 64 * 512, Vg + (t + 1) * 64);
;             }
;             const LAS unsigned char* Qs = lds + 2 * ABUF + wid * (32 * QROW) + r32 * QROW + hi * 16;
;             int kxh = (kx >> 1) << 5, vxh = (vx >> 1) << 5, kq = cb + r32 * KROW + ((hi ^ (kx & 1)) << 4), vq = cb + KBUF + r32 * VROW + ((hi ^ (vx & 1)) << 4);
;             asm volatile("" : "+v"(kxh), "+v"(vxh), "+v"(kq), "+v"(vq));
;             const LAS unsigned char* Kb = lds + kq;
;             const LAS unsigned char* Vb = lds + vq;
; #pragma unroll
;             for (int m = 0; m < 2; ++m) {
;                 f32x16 s0, s1;
; #pragma unroll
;                 for (int i = 0; i < 16; ++i) { s0[i] = 0.f; s1[i] = 0.f; }
; #pragma unroll
;                 for (int d0 = 0; d0 < 4; ++d0) {
;                     const int kpos = ((m * 4 + d0) << 5) ^ kxh;
;                     const bf16x8 k0 = *(const LAS bf16x8*)(Kb + kpos), k1 = *(const LAS bf16x8*)(Kb + 32 * KROW + kpos);
;                     const bf16x8 qv = *(const LAS bf16x8*)(Qs + m * 128 + d0 * 32);
;                     s0 = MFMA32(k0, qv, s0); s1 = MFMA32(k1, qv, s1);
;                 }
;                 __builtin_amdgcn_sched_barrier(0);
;                 float ls = 0.f, ls2 = 0.f;
; #pragma unroll
;                 for (int i = 0; i < 16; ++i) { float e0 = __builtin_amdgcn_exp2f(s0[i]), e1 = __builtin_amdgcn_exp2f(s1[i]); asm volatile("" : "+v"(e0), "+v"(e1)); s0[i] = e0; s1[i] = e1; ls += e0; ls2 += e1; }
;                 ls += ls2;
;                 l[m] += ls;
;                 const bf16x8 p0 = packp(s0, 0), p1 = packp(s0, 1), p2 = packp(s1, 0), p3 = packp(s1, 1);
; #pragma unroll
;                 for (int db = 0; db < 4; ++db) {
;                     const LAS unsigned char* vb = Vb + db * 32 * VROW;
;                     const bf16x8 v0 = *(const LAS bf16x8*)(vb + (0 ^ vxh)), v1 = *(const LAS bf16x8*)(vb + (32 ^ vxh)), v2 = *(const LAS bf16x8*)(vb + (64 ^ vxh)), v3 = *(const LAS bf16x8*)(vb + (96 ^ vxh));
;                     o[m][db] = MFMA32(v0, p0, o[m][db]); o[m][db] = MFMA32(v1, p1, o[m][db]); o[m][db] = MFMA32(v2, p2, o[m][db]); o[m][db] = MFMA32(v3, p3, o[m][db]);
	ds_read_b128 v[144:147], v196 offset:32768
	ds_read_b128 v[148:151], v197 offset:32768
	ds_read_b128 v[152:155], v198 offset:32768
	ds_read_b128 v[156:159], v199 offset:32768
	ds_read_b128 v[164:167], v196 offset:40960
	ds_read_b128 v[168:171], v197 offset:40960
	ds_read_b128 v[172:175], v198 offset:40960
	ds_read_b128 v[212:215], v199 offset:40960
	v_mfma_f32_32x32x16_bf16 v[96:111], v[216:219], v[176:179], v[96:111]
	v_mfma_f32_32x32x16_bf16 v[64:79], v[238:241], v[176:179], v[64:79]
	v_mfma_f32_32x32x16_bf16 v[32:47], v[220:223], v[176:179], v[32:47]
	v_mfma_f32_32x32x16_bf16 v[0:15], v[242:245], v[176:179], v[0:15]
	s_waitcnt lgkmcnt(7)
	v_mfma_f32_32x32x16_bf16 v[128:143], v[144:147], v[180:183], 0
	ds_read_b128 v[216:219], v228 offset:128
	s_mov_b32 m0, s22
	s_nop 0
	global_load_lds_dwordx4 v208, s[6:7]
	s_waitcnt lgkmcnt(7)
	v_mfma_f32_32x32x16_bf16 v[128:143], v[148:151], v[184:187], v[128:143]
	ds_read_b128 v[220:223], v228 offset:160
	s_mov_b32 m0, s24
	s_nop 0
	global_load_lds_dwordx4 v209, s[2:3]
	s_waitcnt lgkmcnt(7)
	v_mfma_f32_32x32x16_bf16 v[128:143], v[152:155], v[188:191], v[128:143]
	ds_read_b128 v[224:227], v228 offset:192
	s_mov_b32 m0, s26
	s_nop 0
	global_load_lds_dwordx4 v210, s[6:7]
	s_waitcnt lgkmcnt(7)
	v_mfma_f32_32x32x16_bf16 v[128:143], v[156:159], v[192:195], v[128:143]
	ds_read_b128 v[234:237], v228 offset:224
	s_mov_b32 m0, s27
	s_nop 0
	global_load_lds_dwordx4 v211, s[2:3]
	s_add_u32 s6, s6, 0x10000
	s_addc_u32 s7, s7, 0
	s_add_u32 s2, s2, 0x80
	s_addc_u32 s3, s3, 0
	s_waitcnt lgkmcnt(7)
	v_mfma_f32_32x32x16_bf16 v[144:159], v[164:167], v[180:183], 0
	ds_read_b128 v[180:183], v200 offset:32768
	ds_read_b128 v[238:241], v200 offset:40960
	v_exp_f32_e32 v128, v128
	v_exp_f32_e32 v129, v129
	v_add_f32_e32 v162, v162, v128
	v_exp_f32_e32 v130, v130
	s_waitcnt lgkmcnt(8)
	v_mfma_f32_32x32x16_bf16 v[144:159], v[168:171], v[184:187], v[144:159]
	ds_read_b128 v[184:187], v201 offset:32768
	ds_read_b128 v[242:245], v201 offset:40960
	v_add_f32_e32 v162, v162, v129
	v_exp_f32_e32 v131, v131
	v_add_f32_e32 v162, v162, v130
	v_cvt_pk_bf16_f32 v128, v128, v129
	s_waitcnt lgkmcnt(9)
	v_mfma_f32_32x32x16_bf16 v[144:159], v[172:175], v[188:191], v[144:159]
	ds_read_b128 v[188:191], v202 offset:32768
	ds_read_b128 v[246:249], v202 offset:40960
	v_exp_f32_e32 v132, v132
	v_add_f32_e32 v162, v162, v131
	v_exp_f32_e32 v133, v133
	v_add_f32_e32 v162, v162, v132
	s_waitcnt lgkmcnt(10)
	v_mfma_f32_32x32x16_bf16 v[144:159], v[212:215], v[192:195], v[144:159]
	ds_read_b128 v[192:195], v203 offset:32768
	ds_read_b128 v[212:215], v203 offset:40960
	v_cvt_pk_bf16_f32 v129, v130, v131
	v_exp_f32_e32 v134, v134
	v_add_f32_e32 v162, v162, v133
	v_exp_f32_e32 v135, v135
	s_waitcnt lgkmcnt(7)
	v_mfma_f32_32x32x16_bf16 v[164:179], v[180:183], v[216:219], 0
	ds_read_b128 v[250:253], v204 offset:32768
	v_add_f32_e32 v162, v162, v134
	v_cvt_pk_bf16_f32 v130, v132, v133
	v_exp_f32_e32 v136, v136
	v_add_f32_e32 v162, v162, v135
	s_waitcnt lgkmcnt(6)
	v_mfma_f32_32x32x16_bf16 v[164:179], v[184:187], v[220:223], v[164:179]
	v_exp_f32_e32 v137, v137
	v_add_f32_e32 v162, v162, v136
	v_cvt_pk_bf16_f32 v131, v134, v135
	v_exp_f32_e32 v138, v138
	s_waitcnt lgkmcnt(4)
	v_mfma_f32_32x32x16_bf16 v[164:179], v[188:191], v[224:227], v[164:179]
	v_add_f32_e32 v162, v162, v137
	v_exp_f32_e32 v139, v139
	v_add_f32_e32 v162, v162, v138
	v_cvt_pk_bf16_f32 v132, v136, v137
	s_waitcnt lgkmcnt(2)
	v_mfma_f32_32x32x16_bf16 v[164:179], v[192:195], v[234:237], v[164:179]
	v_exp_f32_e32 v140, v140
	v_add_f32_e32 v162, v162, v139
	v_exp_f32_e32 v141, v141
	v_add_f32_e32 v162, v162, v140
	v_mfma_f32_32x32x16_bf16 v[180:195], v[238:241], v[216:219], 0
	ds_read_b128 v[216:219], v204 offset:36864
	ds_read_b128 v[238:241], v204 offset:40960
	v_cvt_pk_bf16_f32 v133, v138, v139
	v_exp_f32_e32 v142, v142
	v_add_f32_e32 v162, v162, v141
	v_exp_f32_e32 v143, v143
	v_mfma_f32_32x32x16_bf16 v[180:195], v[242:245], v[220:223], v[180:195]
	ds_read_b128 v[220:223], v204 offset:45056
	ds_read_b128 v[242:245], v205 offset:32768
	v_add_f32_e32 v162, v162, v142
	v_cvt_pk_bf16_f32 v134, v140, v141
	v_add_f32_e32 v162, v162, v143
	v_cvt_pk_bf16_f32 v135, v142, v143
	v_mfma_f32_32x32x16_bf16 v[180:195], v[246:249], v[224:227], v[180:195]
	ds_read_b128 v[224:227], v205 offset:36864
	ds_read_b128 v[246:249], v205 offset:40960
	v_exp_f32_e32 v144, v144
	v_exp_f32_e32 v145, v145
	v_add_f32_e32 v162, v162, v144
	v_exp_f32_e32 v146, v146
	s_waitcnt lgkmcnt(7)
	v_mfma_f32_32x32x16_bf16 v[180:195], v[212:215], v[234:237], v[180:195]
	ds_read_b128 v[212:215], v205 offset:45056
	ds_read_b128 v[234:237], v206 offset:32768
	v_add_f32_e32 v162, v162, v145
	v_exp_f32_e32 v147, v147
	v_add_f32_e32 v162, v162, v146
	v_cvt_pk_bf16_f32 v136, v144, v145
	s_waitcnt lgkmcnt(8)
	v_mfma_f32_32x32x16_bf16 v[112:127], v[250:253], v[128:131], v[112:127]
	ds_read_b128 v[250:253], v206 offset:36864
	v_exp_f32_e32 v148, v148
	v_add_f32_e32 v162, v162, v147
	v_exp_f32_e32 v149, v149
	v_add_f32_e32 v162, v162, v148
	s_waitcnt lgkmcnt(8)
	v_mfma_f32_32x32x16_bf16 v[80:95], v[216:219], v[128:131], v[80:95]
	ds_read_b128 v[216:219], v206 offset:40960
	v_cvt_pk_bf16_f32 v137, v146, v147
	v_exp_f32_e32 v150, v150
	v_add_f32_e32 v162, v162, v149
	v_exp_f32_e32 v151, v151
	s_waitcnt lgkmcnt(8)
	v_mfma_f32_32x32x16_bf16 v[48:63], v[238:241], v[128:131], v[48:63]
	ds_read_b128 v[238:241], v206 offset:45056
	v_add_f32_e32 v162, v162, v150
	v_cvt_pk_bf16_f32 v138, v148, v149
	v_exp_f32_e32 v152, v152
	v_add_f32_e32 v162, v162, v151
	s_waitcnt lgkmcnt(8)
; #define LAS __attribute__((address_space(3)))
; #define MFMA32(a, b, c) __builtin_amdgcn_mfma_f32_32x32x16_bf16((a), (b), (c), 0, 0, 0)
; __device__ __forceinline__ void attn_phase_fast(LAS unsigned char* lds, const bf16_t* q, const bf16_t* k, const bf16_t* vT, bf16_t* mixed, float lam, const int wave_s) {
;     ...
;                 for (int i = 0; i < 16; ++i) { float e0 = __builtin_amdgcn_exp2f(s0[i]), e1 = __builtin_amdgcn_exp2f(s1[i]); asm volatile("" : "+v"(e0), "+v"(e1)); s0[i] = e0; s1[i] = e1; ls += e0; ls2 += e1; }
;                 ls += ls2;
;                 l[m] += ls;
;                 const bf16x8 p0 = packp(s0, 0), p1 = packp(s0, 1), p2 = packp(s1, 0), p3 = packp(s1, 1);
; #pragma unroll
;                 for (int db = 0; db < 4; ++db) {
;                     const LAS unsigned char* vb = Vb + db * 32 * VROW;
;                     const bf16x8 v0 = *(const LAS bf16x8*)(vb + (0 ^ vxh)), v1 = *(const LAS bf16x8*)(vb + (32 ^ vxh)), v2 = *(const LAS bf16x8*)(vb + (64 ^ vxh)), v3 = *(const LAS bf16x8*)(vb + (96 ^ vxh));
;                     o[m][db] = MFMA32(v0, p0, o[m][db]); o[m][db] = MFMA32(v1, p1, o[m][db]); o[m][db] = MFMA32(v2, p2, o[m][db]); o[m][db] = MFMA32(v3, p3, o[m][db]);
;                     if (db == 1) __builtin_amdgcn_sched_barrier(0);
;                 }
;                 __builtin_amdgcn_sched_barrier(0);
;             }
;             asm volatile("s_waitcnt vmcnt(0)" ::: "memory");
;             __syncthreads();
	v_mfma_f32_32x32x16_bf16 v[16:31], v[220:223], v[128:131], v[16:31]
	ds_read_b128 v[220:223], v207 offset:32768
	v_exp_f32_e32 v153, v153
	v_add_f32_e32 v162, v162, v152
	v_cvt_pk_bf16_f32 v139, v150, v151
	v_exp_f32_e32 v154, v154
	s_waitcnt lgkmcnt(8)
	v_mfma_f32_32x32x16_bf16 v[112:127], v[242:245], v[132:135], v[112:127]
	ds_read_b128 v[242:245], v207 offset:36864
	v_add_f32_e32 v162, v162, v153
	v_exp_f32_e32 v155, v155
	v_add_f32_e32 v162, v162, v154
	v_cvt_pk_bf16_f32 v140, v152, v153
	s_waitcnt lgkmcnt(8)
	v_mfma_f32_32x32x16_bf16 v[80:95], v[224:227], v[132:135], v[80:95]
	ds_read_b128 v[224:227], v207 offset:40960
	v_exp_f32_e32 v156, v156
	v_add_f32_e32 v162, v162, v155
	v_exp_f32_e32 v157, v157
	v_add_f32_e32 v162, v162, v156
	s_waitcnt lgkmcnt(8)
	v_mfma_f32_32x32x16_bf16 v[48:63], v[246:249], v[132:135], v[48:63]
	ds_read_b128 v[246:249], v207 offset:45056
	v_cvt_pk_bf16_f32 v141, v154, v155
	v_exp_f32_e32 v158, v158
	v_add_f32_e32 v162, v162, v157
	v_exp_f32_e32 v159, v159
	s_waitcnt lgkmcnt(8)
	v_mfma_f32_32x32x16_bf16 v[16:31], v[212:215], v[132:135], v[16:31]
	ds_read_b128 v[212:215], v204 offset:32768
	v_add_f32_e32 v162, v162, v158
	v_cvt_pk_bf16_f32 v142, v156, v157
	v_add_f32_e32 v162, v162, v159
	v_cvt_pk_bf16_f32 v143, v158, v159
	s_waitcnt lgkmcnt(8)
	v_mfma_f32_32x32x16_bf16 v[112:127], v[234:237], v[136:139], v[112:127]
	ds_read_b128 v[234:237], v204 offset:36864
	v_exp_f32_e32 v164, v164
	v_exp_f32_e32 v165, v165
	v_add_f32_e32 v163, v163, v164
	v_exp_f32_e32 v166, v166
	s_waitcnt lgkmcnt(8)
	v_mfma_f32_32x32x16_bf16 v[80:95], v[250:253], v[136:139], v[80:95]
	ds_read_b128 v[250:253], v204 offset:40960
	v_add_f32_e32 v163, v163, v165
	v_exp_f32_e32 v167, v167
	v_add_f32_e32 v163, v163, v166
	v_cvt_pk_bf16_f32 v164, v164, v165
	s_waitcnt lgkmcnt(8)
	v_mfma_f32_32x32x16_bf16 v[48:63], v[216:219], v[136:139], v[48:63]
	ds_read_b128 v[216:219], v204 offset:45056
	v_exp_f32_e32 v168, v168
	v_add_f32_e32 v163, v163, v167
	v_exp_f32_e32 v169, v169
	v_add_f32_e32 v163, v163, v168
	s_waitcnt lgkmcnt(8)
	v_mfma_f32_32x32x16_bf16 v[16:31], v[238:241], v[136:139], v[16:31]
	ds_read_b128 v[238:241], v205 offset:32768
	v_cvt_pk_bf16_f32 v165, v166, v167
	v_exp_f32_e32 v170, v170
	v_add_f32_e32 v163, v163, v169
	v_exp_f32_e32 v171, v171
	s_waitcnt lgkmcnt(8)
	v_mfma_f32_32x32x16_bf16 v[112:127], v[220:223], v[140:143], v[112:127]
	ds_read_b128 v[220:223], v205 offset:36864
	v_add_f32_e32 v163, v163, v170
	v_cvt_pk_bf16_f32 v166, v168, v169
	v_exp_f32_e32 v172, v172
	v_add_f32_e32 v163, v163, v171
	s_waitcnt lgkmcnt(8)
	v_mfma_f32_32x32x16_bf16 v[80:95], v[242:245], v[140:143], v[80:95]
	ds_read_b128 v[242:245], v205 offset:40960
	v_exp_f32_e32 v173, v173
	v_add_f32_e32 v163, v163, v172
	v_cvt_pk_bf16_f32 v167, v170, v171
	v_exp_f32_e32 v174, v174
	s_waitcnt lgkmcnt(8)
	v_mfma_f32_32x32x16_bf16 v[48:63], v[224:227], v[140:143], v[48:63]
	ds_read_b128 v[224:227], v205 offset:45056
	v_add_f32_e32 v163, v163, v173
	v_exp_f32_e32 v175, v175
	v_add_f32_e32 v163, v163, v174
	v_cvt_pk_bf16_f32 v168, v172, v173
	s_waitcnt lgkmcnt(8)
	v_mfma_f32_32x32x16_bf16 v[16:31], v[246:249], v[140:143], v[16:31]
	ds_read_b128 v[246:249], v206 offset:32768
	v_exp_f32_e32 v176, v176
	v_add_f32_e32 v163, v163, v175
	v_exp_f32_e32 v177, v177
	v_add_f32_e32 v163, v163, v176
	s_waitcnt lgkmcnt(8)
	v_mfma_f32_32x32x16_bf16 v[96:111], v[212:215], v[164:167], v[96:111]
	ds_read_b128 v[212:215], v206 offset:36864
	v_cvt_pk_bf16_f32 v169, v174, v175
	v_exp_f32_e32 v178, v178
	v_add_f32_e32 v163, v163, v177
	v_exp_f32_e32 v179, v179
	s_waitcnt lgkmcnt(8)
	v_mfma_f32_32x32x16_bf16 v[64:79], v[234:237], v[164:167], v[64:79]
	ds_read_b128 v[234:237], v206 offset:40960
	v_add_f32_e32 v163, v163, v178
	v_cvt_pk_bf16_f32 v170, v176, v177
	v_add_f32_e32 v163, v163, v179
	v_cvt_pk_bf16_f32 v171, v178, v179
	s_waitcnt lgkmcnt(8)
	v_mfma_f32_32x32x16_bf16 v[32:47], v[250:253], v[164:167], v[32:47]
	ds_read_b128 v[250:253], v206 offset:45056
	v_exp_f32_e32 v180, v180
	v_exp_f32_e32 v181, v181
	v_add_f32_e32 v163, v163, v180
	v_exp_f32_e32 v182, v182
	s_waitcnt lgkmcnt(8)
	v_mfma_f32_32x32x16_bf16 v[0:15], v[216:219], v[164:167], v[0:15]
	ds_read_b128 v[216:219], v207 offset:32768
	v_add_f32_e32 v163, v163, v181
	v_exp_f32_e32 v183, v183
	v_add_f32_e32 v163, v163, v182
	v_cvt_pk_bf16_f32 v172, v180, v181
	s_waitcnt lgkmcnt(8)
	v_mfma_f32_32x32x16_bf16 v[96:111], v[238:241], v[168:171], v[96:111]
	ds_read_b128 v[238:241], v207 offset:36864
	v_exp_f32_e32 v184, v184
	v_add_f32_e32 v163, v163, v183
	v_exp_f32_e32 v185, v185
	v_add_f32_e32 v163, v163, v184
	s_waitcnt lgkmcnt(8)
	v_mfma_f32_32x32x16_bf16 v[64:79], v[220:223], v[168:171], v[64:79]
	ds_read_b128 v[220:223], v207 offset:40960
	v_cvt_pk_bf16_f32 v173, v182, v183
	v_exp_f32_e32 v186, v186
	v_add_f32_e32 v163, v163, v185
	v_exp_f32_e32 v187, v187
	s_waitcnt lgkmcnt(8)
	v_mfma_f32_32x32x16_bf16 v[32:47], v[242:245], v[168:171], v[32:47]
	ds_read_b128 v[242:245], v207 offset:45056
	v_add_f32_e32 v163, v163, v186
	v_cvt_pk_bf16_f32 v174, v184, v185
	v_exp_f32_e32 v188, v188
	v_add_f32_e32 v163, v163, v187
	s_waitcnt lgkmcnt(8)
	v_mfma_f32_32x32x16_bf16 v[0:15], v[224:227], v[168:171], v[0:15]
	v_exp_f32_e32 v189, v189
	v_add_f32_e32 v163, v163, v188
	v_cvt_pk_bf16_f32 v175, v186, v187
	v_exp_f32_e32 v190, v190
	s_waitcnt lgkmcnt(7)
	v_mfma_f32_32x32x16_bf16 v[96:111], v[246:249], v[172:175], v[96:111]
	v_add_f32_e32 v163, v163, v189
	v_exp_f32_e32 v191, v191
	v_add_f32_e32 v163, v163, v190
	v_cvt_pk_bf16_f32 v176, v188, v189
	s_waitcnt lgkmcnt(6)
	v_mfma_f32_32x32x16_bf16 v[64:79], v[212:215], v[172:175], v[64:79]
	v_exp_f32_e32 v192, v192
	v_add_f32_e32 v163, v163, v191
	v_exp_f32_e32 v193, v193
	v_add_f32_e32 v163, v163, v192
	s_waitcnt lgkmcnt(5)
	v_mfma_f32_32x32x16_bf16 v[32:47], v[234:237], v[172:175], v[32:47]
	v_cvt_pk_bf16_f32 v177, v190, v191
	v_exp_f32_e32 v194, v194
	v_add_f32_e32 v163, v163, v193
	v_exp_f32_e32 v195, v195
	s_waitcnt lgkmcnt(4)
	v_mfma_f32_32x32x16_bf16 v[0:15], v[250:253], v[172:175], v[0:15]
	v_add_f32_e32 v163, v163, v194
	v_cvt_pk_bf16_f32 v178, v192, v193
	v_add_f32_e32 v163, v163, v195
	v_cvt_pk_bf16_f32 v179, v194, v195
	ds_read_b128 v[180:183], v228
	ds_read_b128 v[184:187], v228 offset:32
	ds_read_b128 v[188:191], v228 offset:64
	ds_read_b128 v[192:195], v228 offset:96
	s_waitcnt lgkmcnt(4)
	s_waitcnt vmcnt(0)
	s_add_i32 s44, s44, 2
	s_cmp_gt_u32 s44, s45
	s_barrier
; __device__ __forceinline__ void attn_phase_fast(LAS unsigned char* lds, const bf16_t* q, const bf16_t* k, const bf16_t* vT, bf16_t* mixed, float lam, const int wave_s) {
;     ...
;         const float l0 = l[0] + __shfl_xor(l[0], 32), l1 = l[1] + __shfl_xor(l[1], 32);
;         const float c0 = 1.0f / l0, c1 = lam / l1;
;         float ss = 0.f;
; #pragma unroll
;         for (int db = 0; db < 4; ++db)
; #pragma unroll
;             for (int i = 0; i < 16; ++i) { const float v = o[0][db][i] * c0 - o[1][db][i] * c1; o[0][db][i] = v; ss += v * v; }
	s_cbranch_scc0 .Lattn_tile_loop
	v_mfma_f32_32x32x16_bf16 v[96:111], v[216:219], v[176:179], v[96:111]
	v_mfma_f32_32x32x16_bf16 v[64:79], v[238:241], v[176:179], v[64:79]
	v_mfma_f32_32x32x16_bf16 v[32:47], v[220:223], v[176:179], v[32:47]
	v_mfma_f32_32x32x16_bf16 v[0:15], v[242:245], v[176:179], v[0:15]
	s_mov_b32 m0, s50
	s_waitcnt lgkmcnt(0)
	v_and_b32_e32 v129, 64, v231
	v_xor_b32_e32 v128, 32, v231
	v_add_u32_e32 v129, 64, v129
	v_cmp_lt_i32_e32 vcc, v128, v129
	s_nop 1
	v_cndmask_b32_e32 v128, v231, v128, vcc
	v_lshlrev_b32_e32 v130, 2, v128
	v_mov_b32_e32 v128, v162
	v_mov_b32_e32 v129, v163
	ds_bpermute_b32 v132, v130, v128
	ds_bpermute_b32 v133, v130, v129
	s_lshl_b32 s0, s0, 1
	s_add_i32 s43, s43, s82
	s_cmpk_gt_i32 s43, 0x7ff
	s_waitcnt lgkmcnt(0)
	v_pk_add_f32 v[128:129], v[128:129], v[132:133]
	s_nop 0
	v_div_scale_f32 v131, s[2:3], v129, v129, v229
	v_rcp_f32_e32 v132, v131
	s_nop 0
	v_fma_f32 v133, -v131, v132, 1.0
	v_fmac_f32_e32 v132, v133, v132
	v_div_scale_f32 v133, vcc, v229, v129, v229
	v_mul_f32_e32 v134, v133, v132
	v_fma_f32 v135, -v131, v134, v133
	v_fmac_f32_e32 v134, v135, v132
	v_fma_f32 v131, -v131, v134, v133
	v_div_scale_f32 v133, s[2:3], v128, v128, 1.0
	v_rcp_f32_e32 v135, v133
	v_div_fmas_f32 v131, v131, v132, v134
	v_div_fixup_f32 v129, v131, v129, v229
	v_fma_f32 v131, -v133, v135, 1.0
	v_fmac_f32_e32 v135, v131, v135
	v_div_scale_f32 v131, vcc, 1.0, v128, 1.0
	v_mul_f32_e32 v132, v131, v135
	v_fma_f32 v134, -v133, v132, v131
	v_fmac_f32_e32 v132, v134, v135
	v_fma_f32 v131, -v133, v132, v131
	v_div_fmas_f32 v131, v131, v135, v132
	v_div_fixup_f32 v128, v131, v128, 1.0
	v_mul_f32_e32 v96, v96, v129
	v_fma_f32 v112, v112, v128, -v96
	v_mul_f32_e32 v132, v112, v112
	v_mul_f32_e32 v97, v97, v129
	v_fma_f32 v113, v113, v128, -v97
	v_fmac_f32_e32 v132, v113, v113
	v_mul_f32_e32 v98, v98, v129
	v_fma_f32 v114, v114, v128, -v98
	v_fmac_f32_e32 v132, v114, v114
	v_mul_f32_e32 v99, v99, v129
	v_fma_f32 v115, v115, v128, -v99
	v_fmac_f32_e32 v132, v115, v115
	v_mul_f32_e32 v100, v100, v129
	v_fma_f32 v116, v116, v128, -v100
	v_fmac_f32_e32 v132, v116, v116
	v_mul_f32_e32 v101, v101, v129
	v_fma_f32 v117, v117, v128, -v101
	v_fmac_f32_e32 v132, v117, v117
	v_mul_f32_e32 v102, v102, v129
	v_fma_f32 v118, v118, v128, -v102
	v_fmac_f32_e32 v132, v118, v118
	v_mul_f32_e32 v103, v103, v129
	v_fma_f32 v119, v119, v128, -v103
	v_fmac_f32_e32 v132, v119, v119
	v_mul_f32_e32 v104, v104, v129
	v_fma_f32 v120, v120, v128, -v104
	v_fmac_f32_e32 v132, v120, v120
	v_mul_f32_e32 v105, v105, v129
	v_fma_f32 v121, v121, v128, -v105
	v_fmac_f32_e32 v132, v121, v121
	v_mul_f32_e32 v106, v106, v129
	v_fma_f32 v122, v122, v128, -v106
	v_fmac_f32_e32 v132, v122, v122
	v_mul_f32_e32 v107, v107, v129
	v_fma_f32 v123, v123, v128, -v107
	v_fmac_f32_e32 v132, v123, v123
	v_mul_f32_e32 v108, v108, v129
	v_fma_f32 v124, v124, v128, -v108
	v_fmac_f32_e32 v132, v124, v124
	v_mul_f32_e32 v109, v109, v129
	v_fma_f32 v125, v125, v128, -v109
	v_fmac_f32_e32 v132, v125, v125
	v_mul_f32_e32 v110, v110, v129
	v_fma_f32 v126, v126, v128, -v110
	v_fmac_f32_e32 v132, v126, v126
	v_mul_f32_e32 v111, v111, v129
	v_fma_f32 v127, v127, v128, -v111
	v_fmac_f32_e32 v132, v127, v127
	v_mul_f32_e32 v64, v64, v129
	v_fma_f32 v80, v80, v128, -v64
	v_fmac_f32_e32 v132, v80, v80
	v_mul_f32_e32 v65, v65, v129
	v_fma_f32 v81, v81, v128, -v65
	v_fmac_f32_e32 v132, v81, v81
	v_mul_f32_e32 v66, v66, v129
	v_fma_f32 v82, v82, v128, -v66
	v_fmac_f32_e32 v132, v82, v82
	v_mul_f32_e32 v67, v67, v129
	v_fma_f32 v83, v83, v128, -v67
	v_fmac_f32_e32 v132, v83, v83
	v_mul_f32_e32 v68, v68, v129
	v_fma_f32 v84, v84, v128, -v68
	v_fmac_f32_e32 v132, v84, v84
	v_mul_f32_e32 v69, v69, v129
	v_fma_f32 v85, v85, v128, -v69
	v_fmac_f32_e32 v132, v85, v85
	v_mul_f32_e32 v70, v70, v129
	v_fma_f32 v86, v86, v128, -v70
	v_fmac_f32_e32 v132, v86, v86
	v_mul_f32_e32 v71, v71, v129
	v_fma_f32 v87, v87, v128, -v71
	v_fmac_f32_e32 v132, v87, v87
	v_mul_f32_e32 v72, v72, v129
	v_fma_f32 v88, v88, v128, -v72
	v_fmac_f32_e32 v132, v88, v88
	v_mul_f32_e32 v73, v73, v129
	v_fma_f32 v89, v89, v128, -v73
	v_fmac_f32_e32 v132, v89, v89
	v_mul_f32_e32 v74, v74, v129
	v_fma_f32 v90, v90, v128, -v74
	v_fmac_f32_e32 v132, v90, v90
	v_mul_f32_e32 v75, v75, v129
	v_fma_f32 v91, v91, v128, -v75
	v_fmac_f32_e32 v132, v91, v91
	v_mul_f32_e32 v76, v76, v129
	v_fma_f32 v92, v92, v128, -v76
	v_fmac_f32_e32 v132, v92, v92
	v_mul_f32_e32 v77, v77, v129
	v_fma_f32 v93, v93, v128, -v77
	v_fmac_f32_e32 v132, v93, v93
	v_mul_f32_e32 v78, v78, v129
	v_fma_f32 v94, v94, v128, -v78
	v_fmac_f32_e32 v132, v94, v94
	v_mul_f32_e32 v79, v79, v129
	v_fma_f32 v95, v95, v128, -v79
	v_fmac_f32_e32 v132, v95, v95
	v_mul_f32_e32 v32, v32, v129
	v_fma_f32 v48, v48, v128, -v32
	v_fmac_f32_e32 v132, v48, v48
	v_mul_f32_e32 v33, v33, v129
	v_fma_f32 v49, v49, v128, -v33
	v_fmac_f32_e32 v132, v49, v49
	v_mul_f32_e32 v34, v34, v129
	v_fma_f32 v50, v50, v128, -v34
	v_fmac_f32_e32 v132, v50, v50
	v_mul_f32_e32 v35, v35, v129
	v_fma_f32 v51, v51, v128, -v35
	v_fmac_f32_e32 v132, v51, v51
	v_mul_f32_e32 v36, v36, v129
	v_fma_f32 v52, v52, v128, -v36
	v_fmac_f32_e32 v132, v52, v52
	v_mul_f32_e32 v37, v37, v129
	v_fma_f32 v53, v53, v128, -v37
	v_fmac_f32_e32 v132, v53, v53
	v_mul_f32_e32 v38, v38, v129
	v_fma_f32 v54, v54, v128, -v38
	v_fmac_f32_e32 v132, v54, v54
	v_mul_f32_e32 v39, v39, v129
	v_fma_f32 v55, v55, v128, -v39
	v_fmac_f32_e32 v132, v55, v55
	v_mul_f32_e32 v40, v40, v129
	v_fma_f32 v56, v56, v128, -v40
	v_fmac_f32_e32 v132, v56, v56
	v_mul_f32_e32 v41, v41, v129
	v_fma_f32 v57, v57, v128, -v41
	v_fmac_f32_e32 v132, v57, v57
; __device__ __forceinline__ unsigned cvt_pk_bf16(float lo, float hi) { unsigned r; asm volatile("v_cvt_pk_bf16_f32 %0, %1, %2" : "=v"(r) : "v"(lo), "v"(hi)); return r; }
; __device__ __forceinline__ int lane_id() { int l; asm volatile("v_mbcnt_lo_u32_b32 %0, -1, 0\n\tv_mbcnt_hi_u32_b32 %0, -1, %0" : "=v"(l)); return l; }
; __device__ __forceinline__ void attn_phase_fast(LAS unsigned char* lds, const bf16_t* q, const bf16_t* k, const bf16_t* vT, bf16_t* mixed, float lam, const int wave_s) {
;     ...
;             for (int i = 0; i < 16; ++i) { const float v = o[0][db][i] * c0 - o[1][db][i] * c1; o[0][db][i] = v; ss += v * v; }
;         ss += __shfl_xor(ss, 32);
;         const float rstd = rsqrtf(ss * (1.0f / 128.0f) + EPSV);
;         int lane2 = lane_id(); asm volatile("" : "+v"(lane2));
;         bf16_t* orow = mixed + ((size_t)tok0 + qb * 256 + wid * 32 + (lane2 & 31)) * DM + h * 128 + 4 * (lane2 >> 5);
; #pragma unroll
;         for (int db = 0; db < 4; ++db)
; #pragma unroll
;             for (int i4 = 0; i4 < 4; ++i4) {
;                 u32x2 w; w.x = cvt_pk_bf16(o[0][db][4 * i4] * rstd, o[0][db][4 * i4 + 1] * rstd); w.y = cvt_pk_bf16(o[0][db][4 * i4 + 2] * rstd, o[0][db][4 * i4 + 3] * rstd);
;                 *(u32x2*)(orow + 32 * db + 8 * i4) = w;
	v_mul_f32_e32 v42, v42, v129
	v_fma_f32 v58, v58, v128, -v42
	v_fmac_f32_e32 v132, v58, v58
	v_mul_f32_e32 v43, v43, v129
	v_fma_f32 v59, v59, v128, -v43
	v_fmac_f32_e32 v132, v59, v59
	v_mul_f32_e32 v44, v44, v129
	v_fma_f32 v60, v60, v128, -v44
	v_fmac_f32_e32 v132, v60, v60
	v_mul_f32_e32 v45, v45, v129
	v_fma_f32 v61, v61, v128, -v45
	v_fmac_f32_e32 v132, v61, v61
	v_mul_f32_e32 v46, v46, v129
	v_fma_f32 v62, v62, v128, -v46
	v_fmac_f32_e32 v132, v62, v62
	v_mul_f32_e32 v47, v47, v129
	v_fma_f32 v63, v63, v128, -v47
	v_fmac_f32_e32 v132, v63, v63
	v_mul_f32_e32 v0, v0, v129
	v_fma_f32 v16, v16, v128, -v0
	v_fmac_f32_e32 v132, v16, v16
	v_mul_f32_e32 v1, v1, v129
	v_fma_f32 v17, v17, v128, -v1
	v_fmac_f32_e32 v132, v17, v17
	v_mul_f32_e32 v2, v2, v129
	v_fma_f32 v18, v18, v128, -v2
	v_fmac_f32_e32 v132, v18, v18
	v_mul_f32_e32 v3, v3, v129
	v_fma_f32 v19, v19, v128, -v3
	v_fmac_f32_e32 v132, v19, v19
	v_mul_f32_e32 v4, v4, v129
	v_fma_f32 v20, v20, v128, -v4
	v_fmac_f32_e32 v132, v20, v20
	v_mul_f32_e32 v5, v5, v129
	v_fma_f32 v21, v21, v128, -v5
	v_fmac_f32_e32 v132, v21, v21
	v_mul_f32_e32 v6, v6, v129
	v_fma_f32 v22, v22, v128, -v6
	v_fmac_f32_e32 v132, v22, v22
	v_mul_f32_e32 v7, v7, v129
	v_fma_f32 v23, v23, v128, -v7
	v_fmac_f32_e32 v132, v23, v23
	v_mul_f32_e32 v8, v8, v129
	v_fma_f32 v24, v24, v128, -v8
	v_fmac_f32_e32 v132, v24, v24
	v_mul_f32_e32 v9, v9, v129
	v_fma_f32 v25, v25, v128, -v9
	v_fmac_f32_e32 v132, v25, v25
	v_mul_f32_e32 v10, v10, v129
	v_fma_f32 v26, v26, v128, -v10
	v_fmac_f32_e32 v132, v26, v26
	v_mul_f32_e32 v11, v11, v129
	v_fma_f32 v27, v27, v128, -v11
	v_fmac_f32_e32 v132, v27, v27
	v_mul_f32_e32 v12, v12, v129
	v_fma_f32 v28, v28, v128, -v12
	v_fmac_f32_e32 v132, v28, v28
	v_mul_f32_e32 v13, v13, v129
	v_fma_f32 v29, v29, v128, -v13
	v_fmac_f32_e32 v132, v29, v29
	v_mul_f32_e32 v14, v14, v129
	v_fma_f32 v30, v30, v128, -v14
	v_fmac_f32_e32 v132, v30, v30
	v_mul_f32_e32 v15, v15, v129
	v_fma_f32 v31, v31, v128, -v15
	v_fmac_f32_e32 v132, v31, v31
	s_nop 0
	ds_bpermute_b32 v133, v130, v132
	v_mbcnt_lo_u32_b32 v135, -1, 0
	v_mbcnt_hi_u32_b32 v135, -1, v135
	v_and_b32_e32 v160, 31, v135
	v_ashrrev_i32_e32 v138, 3, v135
	v_and_b32_e32 v138, -4, v138
	v_ashrrev_i32_e32 v139, 31, v138
	v_lshl_add_u64 v[136:137], s[4:5], 0, v[160:161]
	v_lshlrev_b64 v[136:137], 11, v[136:137]
	v_lshl_add_u64 v[136:137], s[20:21], 0, v[136:137]
	v_lshl_add_u64 v[136:137], v[136:137], 0, s[0:1]
	v_lshl_add_u64 v[136:137], v[138:139], 2, v[136:137]
	s_waitcnt lgkmcnt(0)
	v_add_f32_e32 v132, v132, v133
	v_fmamk_f32 v132, v132, 0x3c000000, v232
	v_mul_f32_e32 v133, 0x4b800000, v132
	v_cmp_gt_f32_e32 vcc, s42, v132
	s_nop 1
	v_cndmask_b32_e32 v132, v132, v133, vcc
	v_rsq_f32_e32 v132, v132
	s_nop 0
	v_mul_f32_e32 v133, 0x45800000, v132
	v_cndmask_b32_e32 v134, v132, v133, vcc
	v_mul_f32_e32 v112, v112, v134
	v_mul_f32_e32 v113, v113, v134
	v_mul_f32_e32 v114, v114, v134
	v_mul_f32_e32 v115, v115, v134
	v_mul_f32_e32 v116, v116, v134
	v_mul_f32_e32 v117, v117, v134
	v_mul_f32_e32 v118, v118, v134
	v_mul_f32_e32 v119, v119, v134
	v_cvt_pk_bf16_f32 v96, v112, v113
	v_cvt_pk_bf16_f32 v97, v114, v115
	v_cvt_pk_bf16_f32 v98, v116, v117
	v_cvt_pk_bf16_f32 v99, v118, v119
	s_nop 1
	v_permlane32_swap_b32 v96, v98
	v_permlane32_swap_b32 v97, v99
	global_store_dwordx4 v[136:137], v[96:99], off
	v_mul_f32_e32 v120, v120, v134
	v_mul_f32_e32 v121, v121, v134
	v_mul_f32_e32 v122, v122, v134
	v_mul_f32_e32 v123, v123, v134
	v_mul_f32_e32 v124, v124, v134
	v_mul_f32_e32 v125, v125, v134
	v_mul_f32_e32 v126, v126, v134
	v_mul_f32_e32 v127, v127, v134
	v_cvt_pk_bf16_f32 v104, v120, v121
	v_cvt_pk_bf16_f32 v105, v122, v123
	v_cvt_pk_bf16_f32 v106, v124, v125
	v_cvt_pk_bf16_f32 v107, v126, v127
	s_nop 1
	v_permlane32_swap_b32 v104, v106
	v_permlane32_swap_b32 v105, v107
	global_store_dwordx4 v[136:137], v[104:107], off offset:32
	v_mul_f32_e32 v80, v80, v134
	v_mul_f32_e32 v81, v81, v134
	v_mul_f32_e32 v82, v82, v134
	v_mul_f32_e32 v83, v83, v134
	v_mul_f32_e32 v84, v84, v134
	v_mul_f32_e32 v85, v85, v134
	v_mul_f32_e32 v86, v86, v134
	v_mul_f32_e32 v87, v87, v134
	v_cvt_pk_bf16_f32 v64, v80, v81
	v_cvt_pk_bf16_f32 v65, v82, v83
	v_cvt_pk_bf16_f32 v66, v84, v85
	v_cvt_pk_bf16_f32 v67, v86, v87
	s_nop 1
	v_permlane32_swap_b32 v64, v66
	v_permlane32_swap_b32 v65, v67
	global_store_dwordx4 v[136:137], v[64:67], off offset:64
	v_mul_f32_e32 v88, v88, v134
	v_mul_f32_e32 v89, v89, v134
	v_mul_f32_e32 v90, v90, v134
	v_mul_f32_e32 v91, v91, v134
	v_mul_f32_e32 v92, v92, v134
	v_mul_f32_e32 v93, v93, v134
	v_mul_f32_e32 v94, v94, v134
	v_mul_f32_e32 v95, v95, v134
	v_cvt_pk_bf16_f32 v72, v88, v89
	v_cvt_pk_bf16_f32 v73, v90, v91
	v_cvt_pk_bf16_f32 v74, v92, v93
	v_cvt_pk_bf16_f32 v75, v94, v95
	s_nop 1
	v_permlane32_swap_b32 v72, v74
	v_permlane32_swap_b32 v73, v75
	global_store_dwordx4 v[136:137], v[72:75], off offset:96
	v_mul_f32_e32 v48, v48, v134
	v_mul_f32_e32 v49, v49, v134
	v_mul_f32_e32 v50, v50, v134
	v_mul_f32_e32 v51, v51, v134
	v_mul_f32_e32 v52, v52, v134
	v_mul_f32_e32 v53, v53, v134
	v_mul_f32_e32 v54, v54, v134
	v_mul_f32_e32 v55, v55, v134
	v_cvt_pk_bf16_f32 v32, v48, v49
	v_cvt_pk_bf16_f32 v33, v50, v51
	v_cvt_pk_bf16_f32 v34, v52, v53
	v_cvt_pk_bf16_f32 v35, v54, v55
	s_nop 1
	v_permlane32_swap_b32 v32, v34
	v_permlane32_swap_b32 v33, v35
	global_store_dwordx4 v[136:137], v[32:35], off offset:128
	v_mul_f32_e32 v56, v56, v134
	v_mul_f32_e32 v57, v57, v134
	v_mul_f32_e32 v58, v58, v134
	v_mul_f32_e32 v59, v59, v134
	v_mul_f32_e32 v60, v60, v134
	v_mul_f32_e32 v61, v61, v134
	v_mul_f32_e32 v62, v62, v134
	v_mul_f32_e32 v63, v63, v134
	v_cvt_pk_bf16_f32 v40, v56, v57
	v_cvt_pk_bf16_f32 v41, v58, v59
	v_cvt_pk_bf16_f32 v42, v60, v61
	v_cvt_pk_bf16_f32 v43, v62, v63
	s_nop 1
	v_permlane32_swap_b32 v40, v42
	v_permlane32_swap_b32 v41, v43
	global_store_dwordx4 v[136:137], v[40:43], off offset:160
	v_mul_f32_e32 v16, v16, v134
	v_mul_f32_e32 v17, v17, v134
	v_mul_f32_e32 v18, v18, v134
	v_mul_f32_e32 v19, v19, v134
	v_mul_f32_e32 v20, v20, v134
	v_mul_f32_e32 v21, v21, v134
	v_mul_f32_e32 v22, v22, v134
	v_mul_f32_e32 v23, v23, v134
	v_cvt_pk_bf16_f32 v0, v16, v17
	v_cvt_pk_bf16_f32 v1, v18, v19
	v_cvt_pk_bf16_f32 v2, v20, v21
	v_cvt_pk_bf16_f32 v3, v22, v23
	s_nop 1
	v_permlane32_swap_b32 v0, v2
	v_permlane32_swap_b32 v1, v3
	global_store_dwordx4 v[136:137], v[0:3], off offset:192
	v_mul_f32_e32 v24, v24, v134
	v_mul_f32_e32 v25, v25, v134
	v_mul_f32_e32 v26, v26, v134
	v_mul_f32_e32 v27, v27, v134
	v_mul_f32_e32 v28, v28, v134
	v_mul_f32_e32 v29, v29, v134
	v_mul_f32_e32 v30, v30, v134
	v_mul_f32_e32 v31, v31, v134
	v_cvt_pk_bf16_f32 v8, v24, v25
	v_cvt_pk_bf16_f32 v9, v26, v27
	v_cvt_pk_bf16_f32 v10, v28, v29
	v_cvt_pk_bf16_f32 v11, v30, v31
	s_nop 1
	v_permlane32_swap_b32 v8, v10
	v_permlane32_swap_b32 v9, v11
	global_store_dwordx4 v[136:137], v[8:11], off offset:224
	s_cbranch_scc0 .LBB0_390
